# every MFMA in the A0 tile loop and the A1 second-half stream 8-byte aligned with s_nop fillers (those waves have issue slack)
# baseline (speedup 1.0000x reference)
; #define A_FRAG(dst_, i_) do { if ((i_) < NQK) { dst_ = *(const bf16x8*)(sk + ((i_) & 1) * (32 * KSTR) + ((i_) >> 1) * 32); } \
;           else { dst_ = *(const bf16x8*)(sv + (((i_) - NQK) & 3) * (32 * VSTR) + (((i_) - NQK) >> 2) * 32); } } while (0)
; template <int DQK, int NHQ, int NHKV, bool HAS_META>
; DI void attn_phase(const u16* __restrict__ Q, const u16* __restrict__ K, const u16* __restrict__ Vt, u16* __restrict__ O, const float* __restrict__ qg, const float* __restrict__ kg, char* smem, const int wv) {
;     ...
;     for (int j = 0; j < NT; ++j) {
;       __builtin_amdgcn_s_setprio(0);
;       if (active) {
;     ...
;         for (int i = 0; i < NM; ++i) {
;           if (i < NQK) {
;             if (i & 1) s1 = __builtin_amdgcn_mfma_f32_32x32x16_bf16(ring[i % RING], qf[i >> 1], s1, 0, 0, 0);
;             else       s0 = __builtin_amdgcn_mfma_f32_32x32x16_bf16(ring[i % RING], qf[i >> 1], s0, 0, 0, 0);
;           } else {
;             o[(i - NQK) & 3] = __builtin_amdgcn_mfma_f32_32x32x16_bf16(ring[i % RING], pb[(i - NQK) >> 2], o[(i - NQK) & 3], 0, 0, 0);
;           }
;           if (i + RING < NM) A_FRAG(ring[i % RING], i + RING);
;           __builtin_amdgcn_sched_barrier(0);
;         }
.LBB0_676:
	s_setprio 0
	v_cndmask_b32_e64 v0, 0, 1, s[30:31]
	v_cmp_ne_u32_e64 s[4:5], 1, v0
	s_andn2_b64 vcc, exec, s[30:31]
	s_cbranch_vccnz .LBB0_678
	s_cmp_eq_u32 s59, 0
	s_cbranch_scc1 .Lmy_a0_nodef_loop
	s_nop 0
	v_mfma_f32_32x32x16_bf16 v[96:111], v[238:241], v[132:135], v[96:111]
	v_mfma_f32_32x32x16_bf16 v[80:95], v[242:245], v[132:135], v[80:95]
	v_mfma_f32_32x32x16_bf16 v[64:79], v[246:249], v[132:135], v[64:79]
	v_mfma_f32_32x32x16_bf16 v[48:63], v[250:253], v[132:135], v[48:63]
	v_mfma_f32_32x32x16_bf16 v[96:111], v[226:229], v[136:139], v[96:111]
	v_mfma_f32_32x32x16_bf16 v[80:95], v[222:225], v[136:139], v[80:95]
	v_mfma_f32_32x32x16_bf16 v[64:79], v[10:13], v[136:139], v[64:79]
	v_mfma_f32_32x32x16_bf16 v[48:63], v[6:9], v[136:139], v[48:63]

; #define RAW_BAR() do { asm volatile("s_waitcnt lgkmcnt(0)" ::: "memory"); __builtin_amdgcn_s_barrier(); asm volatile("" ::: "memory"); } while (0)
; #define A_WRITEK(bi_) do { char* b_ = kb0 + (bi_) * KBYTES + kwoff; \
;     _Pragma("unroll") for (int i_ = 0; i_ < NKC; ++i_) *(u32x4*)(b_ + i_ * 128) = rk[i_]; } while (0)
; template <int DQK, int NHQ, int NHKV, bool HAS_META>
; DI void attn_phase(const u16* __restrict__ Q, const u16* __restrict__ K, const u16* __restrict__ Vt, u16* __restrict__ O, const float* __restrict__ qg, const float* __restrict__ kg, char* smem, const int wv) {
;     ...
;       __builtin_amdgcn_s_setprio(2);
;       RAW_BAR();
;       if (j + 2 < NT) A_WRITEK(j & 1);
;       else if (j == NT - 1 && has_next) A_WRITEK(0);
;       if (j + 1 < NT) A_WRITEV((j + 1) & 1);
;       __builtin_amdgcn_sched_barrier(0);
;       if constexpr (EARLY_FETCH) { A_FETCH(j); __builtin_amdgcn_sched_barrier(0); }
;         if (active && j == NT - 1) {
;         const char* svl = vb0 + (j & 1) * VBYTES + r32 * VSTR + hh * 16;
;         bf16x8 vf[4];
; #pragma unroll
;         for (int d = 0; d < 4; ++d) vf[d] = *(const bf16x8*)(svl + d * 32 * VSTR);
; #pragma unroll
;         for (int d = 0; d < 4; ++d) o[d] = __builtin_amdgcn_mfma_f32_32x32x16_bf16(vf[d], pb[0], o[d], 0, 0, 0);
;       } else if (active)
;       {
;         constexpr int NQK = 2 * NS, NM = NQK + 16, RING = (DQK == 128) ? 8 : 6;
;         const char* sk = kb0 + ((j + 1) & 1) * KBYTES + r32 * KSTR + hh * 16;
;         const char* sv = vb0 + (j & 1) * VBYTES + r32 * VSTR + hh * 16;
;         bf16x8 ring[RING];
;     ...
; #pragma unroll
;         for (int i = 0; i < 16; ++i) { s0[i] = 0.f; s1[i] = 0.f; }
; #pragma unroll
;         for (int i = 0; i < RING; ++i) A_FRAG(ring[i], i);
; #pragma unroll
;         for (int i = 0; i < NM; ++i) {
;           if (i < NQK) {
;             if (i & 1) s1 = __builtin_amdgcn_mfma_f32_32x32x16_bf16(ring[i % RING], qf[i >> 1], s1, 0, 0, 0);
;             else       s0 = __builtin_amdgcn_mfma_f32_32x32x16_bf16(ring[i % RING], qf[i >> 1], s0, 0, 0, 0);
;           } else {
;             o[(i - NQK) & 3] = __builtin_amdgcn_mfma_f32_32x32x16_bf16(ring[i % RING], pb[(i - NQK) >> 2], o[(i - NQK) & 3], 0, 0, 0);
;           }
;           if (i + RING < NM) A_FRAG(ring[i % RING], i + RING);
;           __builtin_amdgcn_sched_barrier(0);
;         }
.LBB0_678:
	s_setprio 2
	s_bitcmp1_b32 s59, 0
	s_cselect_b64 s[38:39], -1, 0
	s_and_b64 s[40:41], s[38:39], exec
	s_cselect_b32 s60, 0x6400, 0
	s_add_i32 s61, s59, 1
	s_bitcmp1_b32 s61, 0
	s_cselect_b64 s[40:41], -1, 0
	s_waitcnt lgkmcnt(0)
	s_barrier
	s_and_b64 s[62:63], s[40:41], exec
	v_add_u32_e32 v0, s60, v212
	s_cselect_b32 s62, 0x4800, 0
	s_waitcnt vmcnt(4)
	ds_write_b128 v0, v[116:119]
	s_waitcnt vmcnt(3)
	ds_write_b128 v0, v[120:123] offset:128
	s_waitcnt vmcnt(2)
	ds_write_b128 v0, v[124:127] offset:256
	v_add_u32_e32 v0, s62, v215
	s_waitcnt vmcnt(1)
	ds_write_b128 v0, v[140:143] offset:51200
	s_waitcnt vmcnt(0)
	ds_write_b128 v0, v[144:147] offset:60416
	s_and_b64 vcc, exec, s[4:5]
	s_cbranch_vccnz .LBB0_680
	s_and_b64 s[40:41], s[40:41], exec
	s_cselect_b32 s62, 0x6400, 0
	v_add_u32_e32 v0, s62, v216
	ds_read_b128 v[2:5], v0
	ds_read_b128 v[6:9], v0 offset:32
	ds_read_b128 v[10:13], v0 offset:12800
	ds_read_b128 v[140:143], v0 offset:12832
	ds_read_b128 v[144:147], v0 offset:12864
	ds_read_b128 v[222:225], v0 offset:64
	ds_read_b128 v[226:229], v0 offset:96
	s_and_b64 s[40:41], s[38:39], exec
	s_cselect_b32 s40, 0x4800, 0
	v_add_u32_e32 v14, s40, v217
	s_waitcnt lgkmcnt(6)
	v_mfma_f32_32x32x16_bf16 v[16:31], v[2:5], v[192:195], 0
	s_nop 0
	s_waitcnt lgkmcnt(4)
	v_mfma_f32_32x32x16_bf16 v[32:47], v[10:13], v[192:195], 0
	ds_read_b128 v[2:5], v0 offset:12896
	v_mfma_f32_32x32x16_bf16 v[16:31], v[6:9], v[188:191], v[16:31]
	ds_read_b128 v[10:13], v0 offset:128
	s_nop 0
	s_waitcnt lgkmcnt(5)
	v_mfma_f32_32x32x16_bf16 v[32:47], v[140:143], v[188:191], v[32:47]
	ds_read_b128 v[6:9], v0 offset:12928
	s_nop 0
	s_waitcnt lgkmcnt(4)
	v_mfma_f32_32x32x16_bf16 v[16:31], v[222:225], v[184:187], v[16:31]
	ds_read_b128 v[140:143], v0 offset:160
	v_mfma_f32_32x32x16_bf16 v[32:47], v[144:147], v[184:187], v[32:47]
	ds_read_b128 v[222:225], v0 offset:12960
	s_nop 0
	s_waitcnt lgkmcnt(5)
	v_mfma_f32_32x32x16_bf16 v[16:31], v[226:229], v[180:183], v[16:31]
	ds_read_b128 v[144:147], v0 offset:192
	s_nop 0
	s_waitcnt lgkmcnt(5)
	v_mfma_f32_32x32x16_bf16 v[32:47], v[2:5], v[180:183], v[32:47]
	ds_read_b128 v[226:229], v0 offset:12992
	s_nop 0
	s_waitcnt lgkmcnt(5)
	v_mfma_f32_32x32x16_bf16 v[16:31], v[10:13], v[176:179], v[16:31]
	ds_read_b128 v[2:5], v0 offset:224
	s_nop 0
	s_waitcnt lgkmcnt(5)
	v_mfma_f32_32x32x16_bf16 v[32:47], v[6:9], v[176:179], v[32:47]
	ds_read_b128 v[10:13], v0 offset:13024
	s_nop 0
	s_waitcnt lgkmcnt(5)
	v_mfma_f32_32x32x16_bf16 v[16:31], v[140:143], v[172:175], v[16:31]
	ds_read_b128 v[6:9], v0 offset:256
	s_nop 0
	s_waitcnt lgkmcnt(5)
	v_mfma_f32_32x32x16_bf16 v[32:47], v[222:225], v[172:175], v[32:47]
	ds_read_b128 v[140:143], v0 offset:13056
	s_nop 0
	s_waitcnt lgkmcnt(5)
	v_mfma_f32_32x32x16_bf16 v[16:31], v[144:147], v[168:171], v[16:31]
	ds_read_b128 v[222:225], v0 offset:288
	s_nop 0
	s_waitcnt lgkmcnt(5)
	v_mfma_f32_32x32x16_bf16 v[32:47], v[226:229], v[168:171], v[32:47]
	ds_read_b128 v[144:147], v0 offset:13088
	s_nop 0
	s_waitcnt lgkmcnt(5)
	v_mfma_f32_32x32x16_bf16 v[16:31], v[2:5], v[164:167], v[16:31]
	ds_read_b128 v[226:229], v0 offset:320
	s_nop 0
	s_waitcnt lgkmcnt(5)
	v_mfma_f32_32x32x16_bf16 v[32:47], v[10:13], v[164:167], v[32:47]
	ds_read_b128 v[2:5], v0 offset:13120
	s_nop 0
	s_waitcnt lgkmcnt(5)
	v_mfma_f32_32x32x16_bf16 v[16:31], v[6:9], v[160:163], v[16:31]
	ds_read_b128 v[10:13], v0 offset:352
	s_nop 0
	s_waitcnt lgkmcnt(5)
	v_mfma_f32_32x32x16_bf16 v[32:47], v[140:143], v[160:163], v[32:47]
	ds_read_b128 v[6:9], v0 offset:13152
	s_nop 0
	s_waitcnt lgkmcnt(5)
	v_mfma_f32_32x32x16_bf16 v[16:31], v[222:225], v[156:159], v[16:31]
	ds_read_b128 v[140:143], v14 offset:51200
	s_nop 0
	s_waitcnt lgkmcnt(5)
	v_mfma_f32_32x32x16_bf16 v[32:47], v[144:147], v[156:159], v[32:47]
	ds_read_b128 v[222:225], v14 offset:55808
	s_nop 0
	s_waitcnt lgkmcnt(5)
	v_mfma_f32_32x32x16_bf16 v[16:31], v[226:229], v[152:155], v[16:31]
	ds_read_b128 v[144:147], v14 offset:60416
	s_nop 0
	s_waitcnt lgkmcnt(5)
	v_mfma_f32_32x32x16_bf16 v[32:47], v[2:5], v[152:155], v[32:47]
	ds_read_b128 v[226:229], v14 offset:65024
	s_nop 0
	s_waitcnt lgkmcnt(5)
	v_mfma_f32_32x32x16_bf16 v[16:31], v[10:13], v[148:151], v[16:31]
	ds_read_b128 v[2:5], v14 offset:51232
	s_nop 0
	s_waitcnt lgkmcnt(5)
	v_mfma_f32_32x32x16_bf16 v[32:47], v[6:9], v[148:151], v[32:47]
	ds_read_b128 v[10:13], v14 offset:55840
	s_nop 0
	s_waitcnt lgkmcnt(5)
	v_mfma_f32_32x32x16_bf16 v[96:111], v[140:143], v[112:115], v[96:111]
	ds_read_b128 v[6:9], v14 offset:60448
	s_nop 0
	s_waitcnt lgkmcnt(5)
	v_mfma_f32_32x32x16_bf16 v[80:95], v[222:225], v[112:115], v[80:95]
	ds_read_b128 v[140:143], v14 offset:65056
	s_nop 0
	s_waitcnt lgkmcnt(5)
	v_mfma_f32_32x32x16_bf16 v[64:79], v[144:147], v[112:115], v[64:79]
	ds_read_b128 v[238:241], v14 offset:51264
	ds_read_b128 v[242:245], v14 offset:55872
	s_nop 0
	s_waitcnt lgkmcnt(6)
	v_mfma_f32_32x32x16_bf16 v[48:63], v[226:229], v[112:115], v[48:63]
	ds_read_b128 v[246:249], v14 offset:60480
	ds_read_b128 v[250:253], v14 offset:65088
	s_nop 0
	s_waitcnt lgkmcnt(7)
	v_mfma_f32_32x32x16_bf16 v[96:111], v[2:5], v[128:131], v[96:111]
	ds_read_b128 v[226:229], v14 offset:51296
	ds_read_b128 v[222:225], v14 offset:55904
	s_nop 0
	s_waitcnt lgkmcnt(8)
	v_mfma_f32_32x32x16_bf16 v[80:95], v[10:13], v[128:131], v[80:95]
	ds_read_b128 v[10:13], v14 offset:60512
	s_nop 0
	s_waitcnt lgkmcnt(8)
	v_mfma_f32_32x32x16_bf16 v[64:79], v[6:9], v[128:131], v[64:79]
	ds_read_b128 v[6:9], v14 offset:65120
	s_nop 0
	s_waitcnt lgkmcnt(8)
	v_mfma_f32_32x32x16_bf16 v[48:63], v[140:143], v[128:131], v[48:63]
	s_waitcnt lgkmcnt(0)

; #define B_LOADK(Kb_, tile_) do { const char* kp_ = (const char*)(Kb_) + (size_t)(tile_) * (64 * LDK * 2); const unsigned ko_ = ((tile_) == NT - 1) ? koffL : koff; \
;     _Pragma("unroll") for (int i_ = 0; i_ < NKC; ++i_) rk[i_] = *(const u32x4*)(kp_ + ko_ + i_ * 128); } while (0)
; #define B_LOADV(Vb_, tile_) do { const char* vp_ = (const char*)(Vb_) + (size_t)(tile_) * 128; \
;     rv[0] = *(const u32x4*)(vp_ + voff); rv[1] = *(const u32x4*)(vp_ + voff + 64 * LP * 2); } while (0)
; #define B_WRITEK(bi_) do { char* b_w = kb0 + (bi_) * KBYTES + kwoff; \
;     _Pragma("unroll") for (int i_ = 0; i_ < NKC; ++i_) *(u32x4*)(b_w + i_ * 128) = rk[i_]; } while (0)
; #define B_WRITEV(bi_) do { char* b_w = vb0 + (bi_) * VBYTES + vwoff; \
;     *(u32x4*)(b_w) = rv[0]; *(u32x4*)(b_w + 64 * VSTR) = rv[1]; } while (0)
; template <int NHQ, int NHKV>
; DI void attn_phase_l1(const u16* __restrict__ Q, const u16* __restrict__ K, const u16* __restrict__ Vt, u16* __restrict__ O, const float* __restrict__ qg, char* smem, const int wv) {
;     ...
;       if (j + 2 < NT) B_WRITEK(j & 1);
;       if (j + 1 < NT) B_WRITEV((j + 1) & 1);
;       __builtin_amdgcn_sched_barrier(0);
;       if (j + 3 < NT) B_LOADK(Kb, j + 3);
;       if (j + 2 < NT) B_LOADV(Vb, j + 2);
;     ...
;         constexpr int NQK = 2 * NS, NM = NQK + 16, RING = 8;
;         const char* sk = kb0 + ((j + 1) & 1) * KBYTES + r32 * KSTR + hh * 16;
;         const char* sv = vb0 + (j & 1) * VBYTES + r32 * VSTR + hh * 16;
;         bf16x8 ring[RING];
;         unsigned w_[16]; f32x2 ps2 = {0.f, 0.f};
;     ...
; #pragma unroll
;         for (int i = 0; i < 16; ++i) { s0[i] = 0.f; s1[i] = 0.f; }
; #pragma unroll
;         for (int i = 0; i < RING; ++i) B_FRAG(ring[i], i);
; #pragma unroll
;         for (int i = 0; i < NM; ++i) {
;           if (i < NQK) {
;             if (i & 1) s1 = __builtin_amdgcn_mfma_f32_32x32x16_bf16(ring[i % RING], qf[i >> 1], s1, 0, 0, 0);
;             else       s0 = __builtin_amdgcn_mfma_f32_32x32x16_bf16(ring[i % RING], qf[i >> 1], s0, 0, 0, 0);
;           } else {
;             o[(i - NQK) & 3] = __builtin_amdgcn_mfma_f32_32x32x16_bf16(ring[i % RING], pb[(i - NQK) >> 2], o[(i - NQK) & 3], 0, 0, 0);
;           }
;           if (i + RING < NM) B_FRAG(ring[i % RING], i + RING);
.Lb_body:
	s_add_i32 s27, s42, 1
	s_bitcmp1_b32 s27, 0
	s_cselect_b64 s[20:21], -1, 0
	s_and_b64 s[22:23], s[20:21], exec
	s_cselect_b32 s26, 0x4400, 0
	s_bitcmp1_b32 s42, 0
	s_cselect_b64 s[22:23], -1, 0
	s_and_b64 s[44:45], s[22:23], exec
	s_cselect_b32 s43, 0x4800, 0
	s_and_b64 s[22:23], s[22:23], exec
	s_cselect_b32 s22, 0x4400, 0
	v_add_u32_e32 v164, s22, v205
	ds_read_b128 v[64:67], v164
	ds_read_b128 v[178:181], v164 offset:32
	ds_read_b128 v[182:185], v164 offset:8736
	ds_read_b128 v[186:189], v164 offset:8768
	ds_read_b128 v[190:193], v164 offset:64
	ds_read_b128 v[194:197], v164 offset:96
	ds_read_b128 v[214:217], v164 offset:8800
	s_waitcnt lgkmcnt(6)
	v_mfma_f32_32x32x16_bf16 v[80:95], v[64:67], v[100:103], 0
	ds_read_b128 v[68:71], v164 offset:8704
	ds_read_b128 v[220:223], v164 offset:128
	s_and_b64 s[20:21], s[20:21], exec
	s_cselect_b32 s20, 0x4800, 0
	v_add_u32_e32 v177, s20, v206
	ds_read_b128 v[224:227], v164 offset:8832
	s_nop 0
	s_waitcnt lgkmcnt(2)
	v_mfma_f32_32x32x16_bf16 v[64:79], v[68:71], v[100:103], 0
	v_mfma_f32_32x32x16_bf16 v[80:95], v[178:181], v[108:111], v[80:95]
	ds_read_b128 v[228:231], v164 offset:160
	ds_read_b128 v[178:181], v164 offset:8864
	s_waitcnt vmcnt(0)
	v_add_u32_e32 v238, s26, v203
	ds_write_b128 v238, v[128:131]
	v_mfma_f32_32x32x16_bf16 v[64:79], v[182:185], v[108:111], v[64:79]
	ds_write_b128 v238, v[132:135] offset:128
	v_mfma_f32_32x32x16_bf16 v[80:95], v[190:193], v[96:99], v[80:95]
	ds_read_b128 v[182:185], v164 offset:192
	ds_read_b128 v[190:193], v164 offset:8896
	v_add_u32_e32 v239, s43, v204
	ds_write_b128 v239, v[136:139] offset:34816
	s_nop 0
	v_mfma_f32_32x32x16_bf16 v[64:79], v[186:189], v[96:99], v[64:79]
	ds_write_b128 v239, v[140:143] offset:44032
	v_mfma_f32_32x32x16_bf16 v[80:95], v[194:197], v[104:107], v[80:95]
	ds_read_b128 v[186:189], v164 offset:224
	ds_read_b128 v[194:197], v164 offset:8928
	s_cmp_gt_u32 s27, 61
	s_cbranch_scc1 .Lmy_b_skipk
	s_cmp_eq_u32 s42, 60
	s_cselect_b64 vcc, -1, 0
	s_add_u32 s42, s6, s24
	v_cndmask_b32_e32 v242, v160, v201, vcc
	s_addc_u32 s43, s7, s25
	v_mov_b32_e32 v243, 0
	v_lshl_add_u64 v[240:241], s[42:43], 0, v[242:243]
	v_add_co_u32_e32 v240, vcc, 0x38b18000, v240
	s_nop 1
	v_addc_co_u32_e32 v241, vcc, 0, v241, vcc
	global_load_dwordx4 v[128:131], v[240:241], off
	global_load_dwordx4 v[132:135], v[240:241], off offset:128
.Lmy_b_skipk:
	v_mfma_f32_32x32x16_bf16 v[64:79], v[214:217], v[104:107], v[64:79]
	v_lshl_add_u64 v[240:241], s[6:7], 0, v[174:175]
	v_add_co_u32_e32 v244, vcc, 0x29900000, v240
	s_nop 1
	v_addc_co_u32_e32 v245, vcc, 0, v241, vcc
	v_add_co_u32_e32 v240, vcc, 0x29982000, v240
	s_nop 1
	v_addc_co_u32_e32 v241, vcc, 0, v241, vcc
	global_load_dwordx4 v[136:139], v[244:245], off offset:256
	global_load_dwordx4 v[140:143], v[240:241], off offset:256
	s_nop 0
	s_waitcnt lgkmcnt(11)
	v_mfma_f32_32x32x16_bf16 v[80:95], v[220:223], v[116:119], v[80:95]
	ds_read_b128 v[214:217], v177 offset:34816
	ds_read_b128 v[220:223], v177 offset:39424
	s_nop 0
	s_waitcnt lgkmcnt(11)
	v_mfma_f32_32x32x16_bf16 v[64:79], v[224:227], v[116:119], v[64:79]
	v_mfma_f32_32x32x16_bf16 v[80:95], v[228:231], v[120:123], v[80:95]
	ds_read_b128 v[224:227], v177 offset:44032
	ds_read_b128 v[228:231], v177 offset:48640
	s_nop 0
	s_waitcnt lgkmcnt(9)
	v_mfma_f32_32x32x16_bf16 v[64:79], v[178:181], v[120:123], v[64:79]
	v_mfma_f32_32x32x16_bf16 v[80:95], v[182:185], v[112:115], v[80:95]
	ds_read_b128 v[178:181], v177 offset:34848
	ds_read_b128 v[182:185], v177 offset:39456
	s_nop 0
	s_waitcnt lgkmcnt(7)
	v_mfma_f32_32x32x16_bf16 v[64:79], v[190:193], v[112:115], v[64:79]
	v_mfma_f32_32x32x16_bf16 v[80:95], v[186:189], v[124:127], v[80:95]
	ds_read_b128 v[190:193], v177 offset:44064
	ds_read_b128 v[186:189], v177 offset:48672
	s_nop 0
	s_waitcnt lgkmcnt(7)
	v_mfma_f32_32x32x16_bf16 v[64:79], v[194:197], v[124:127], v[64:79]
	v_mfma_f32_32x32x16_bf16 v[48:63], v[214:217], v[144:147], v[48:63]
	ds_read_b128 v[194:197], v177 offset:34880
	s_nop 0
	s_waitcnt lgkmcnt(7)
	v_mfma_f32_32x32x16_bf16 v[32:47], v[220:223], v[144:147], v[32:47]
	ds_read_b128 v[214:217], v177 offset:39488
	s_nop 0
	s_waitcnt lgkmcnt(7)
	v_mfma_f32_32x32x16_bf16 v[16:31], v[224:227], v[144:147], v[16:31]
	ds_read_b128 v[220:223], v177 offset:44096
	s_nop 0
	s_waitcnt lgkmcnt(7)
	v_mfma_f32_32x32x16_bf16 v[0:15], v[228:231], v[144:147], v[0:15]
	ds_read_b128 v[224:227], v177 offset:48704
	s_nop 0
	s_waitcnt lgkmcnt(7)
	v_mfma_f32_32x32x16_bf16 v[48:63], v[178:181], v[148:151], v[48:63]
	ds_read_b128 v[228:231], v177 offset:34912
	s_nop 0
	s_waitcnt lgkmcnt(7)
	v_mfma_f32_32x32x16_bf16 v[32:47], v[182:185], v[148:151], v[32:47]
	ds_read_b128 v[178:181], v177 offset:39520
	s_nop 0
	s_waitcnt lgkmcnt(7)
	v_mfma_f32_32x32x16_bf16 v[16:31], v[190:193], v[148:151], v[16:31]
	ds_read_b128 v[182:185], v177 offset:44128
	s_nop 0
	s_waitcnt lgkmcnt(7)
	v_mfma_f32_32x32x16_bf16 v[0:15], v[186:189], v[148:151], v[0:15]
	ds_read_b128 v[190:193], v177 offset:48736
	s_nop 0
	s_waitcnt lgkmcnt(6)
	v_mfma_f32_32x32x16_bf16 v[48:63], v[194:197], v[152:155], v[48:63]
	v_mfma_f32_32x32x16_bf16 v[32:47], v[214:217], v[152:155], v[32:47]
	s_nop 0
	s_waitcnt lgkmcnt(4)
	v_mfma_f32_32x32x16_bf16 v[16:31], v[220:223], v[152:155], v[16:31]
	v_mfma_f32_32x32x16_bf16 v[0:15], v[224:227], v[152:155], v[0:15]
	s_nop 0
	s_waitcnt lgkmcnt(2)
	v_mfma_f32_32x32x16_bf16 v[48:63], v[228:231], v[156:159], v[48:63]
	v_mfma_f32_32x32x16_bf16 v[32:47], v[178:181], v[156:159], v[32:47]
	s_nop 0
	s_waitcnt lgkmcnt(0)
	v_mfma_f32_32x32x16_bf16 v[16:31], v[182:185], v[156:159], v[16:31]
	v_mfma_f32_32x32x16_bf16 v[0:15], v[190:193], v[156:159], v[0:15]
	s_waitcnt lgkmcnt(0)
	s_barrier
	s_add_u32 s24, s24, 0x8000
	s_addc_u32 s25, s25, 0
	s_cmp_eq_u32 s27, 62
	v_lshl_add_u64 v[174:175], v[174:175], 0, s[16:17]
	s_cbranch_scc1 .Lb_exit
	s_mov_b32 s42, s27
	s_branch .Lb_top
